# baseline (speedup 1.0000x reference)
.LBB0_380:
	v_lshl_or_b32 v152, s30, 7, v156
	v_readlane_b32 s16, v253, 20
	v_ashrrev_i32_e32 v153, 31, v152
	v_readlane_b32 s17, v253, 21
	v_mul_f32_e32 v118, 0xbfb8aa3b, v118
	v_mul_f32_e32 v114, 0xbfb8aa3b, v114
	v_lshl_add_u64 v[140:141], v[152:153], 2, s[16:17]
	global_load_dwordx4 v[148:151], v[140:141], off offset:16
	s_nop 0
	global_load_dwordx4 v[140:143], v[140:141], off
	v_lshlrev_b64 v[152:153], 1, v[152:153]
	v_mul_f32_e32 v119, 0xbfb8aa3b, v119
	v_mul_f32_e32 v115, 0xbfb8aa3b, v115
	v_mul_f32_e32 v120, 0xbfb8aa3b, v120
	v_mul_f32_e32 v116, 0xbfb8aa3b, v116
	v_mul_f32_e32 v121, 0xbfb8aa3b, v121
	v_mul_f32_e32 v117, 0xbfb8aa3b, v117
	v_exp_f32_e32 v118, v118
	v_exp_f32_e32 v114, v114
	v_exp_f32_e32 v119, v119
	v_exp_f32_e32 v115, v115
	v_exp_f32_e32 v120, v120
	v_exp_f32_e32 v116, v116
	v_exp_f32_e32 v121, v121
	v_exp_f32_e32 v117, v117
	v_add_f32_e32 v118, 1.0, v118
	v_add_f32_e32 v114, 1.0, v114
	v_add_f32_e32 v119, 1.0, v119
	v_add_f32_e32 v115, 1.0, v115
	v_add_f32_e32 v120, 1.0, v120
	v_add_f32_e32 v116, 1.0, v116
	v_add_f32_e32 v121, 1.0, v121
	v_add_f32_e32 v117, 1.0, v117
	v_rcp_f32_e32 v118, v118
	v_rcp_f32_e32 v114, v114
	v_rcp_f32_e32 v119, v119
	v_rcp_f32_e32 v115, v115
	v_rcp_f32_e32 v120, v120
	v_rcp_f32_e32 v116, v116
	v_rcp_f32_e32 v121, v121
	v_rcp_f32_e32 v117, v117
	v_pk_mul_f32 v[118:119], v[126:127], v[118:119]
	v_pk_mul_f32 v[114:115], v[122:123], v[114:115]
	v_pk_mul_f32 v[120:121], v[128:129], v[120:121]
	v_pk_mul_f32 v[116:117], v[124:125], v[116:117]
	v_mul_f32_e32 v102, 0xbfb8aa3b, v102
	v_mul_f32_e32 v98, 0xbfb8aa3b, v98
	v_mul_f32_e32 v103, 0xbfb8aa3b, v103
	v_mul_f32_e32 v99, 0xbfb8aa3b, v99
	v_mul_f32_e32 v104, 0xbfb8aa3b, v104
	v_mul_f32_e32 v100, 0xbfb8aa3b, v100
	v_mul_f32_e32 v105, 0xbfb8aa3b, v105
	v_mul_f32_e32 v101, 0xbfb8aa3b, v101
	v_exp_f32_e32 v102, v102
	v_exp_f32_e32 v98, v98
	v_exp_f32_e32 v103, v103
	v_exp_f32_e32 v99, v99
	v_exp_f32_e32 v104, v104
	v_exp_f32_e32 v100, v100
	v_exp_f32_e32 v105, v105
	v_exp_f32_e32 v101, v101
	v_add_f32_e32 v102, 1.0, v102
	v_add_f32_e32 v98, 1.0, v98
	v_add_f32_e32 v103, 1.0, v103
	v_add_f32_e32 v99, 1.0, v99
	v_add_f32_e32 v104, 1.0, v104
	v_add_f32_e32 v100, 1.0, v100
	v_add_f32_e32 v105, 1.0, v105
	v_add_f32_e32 v101, 1.0, v101
	v_rcp_f32_e32 v102, v102
	v_rcp_f32_e32 v98, v98
	v_rcp_f32_e32 v103, v103
	v_rcp_f32_e32 v99, v99
	v_rcp_f32_e32 v104, v104
	v_rcp_f32_e32 v100, v100
	v_rcp_f32_e32 v105, v105
	v_rcp_f32_e32 v101, v101
	v_pk_mul_f32 v[102:103], v[110:111], v[102:103]
	v_pk_mul_f32 v[98:99], v[106:107], v[98:99]
	v_pk_mul_f32 v[104:105], v[112:113], v[104:105]
	v_pk_mul_f32 v[100:101], v[108:109], v[100:101]
	v_mul_f32_e32 v86, 0xbfb8aa3b, v86
	v_mul_f32_e32 v82, 0xbfb8aa3b, v82
	v_mul_f32_e32 v87, 0xbfb8aa3b, v87
	v_mul_f32_e32 v83, 0xbfb8aa3b, v83
	v_mul_f32_e32 v88, 0xbfb8aa3b, v88
	v_mul_f32_e32 v84, 0xbfb8aa3b, v84
	v_mul_f32_e32 v89, 0xbfb8aa3b, v89
	v_mul_f32_e32 v85, 0xbfb8aa3b, v85
	s_waitcnt vmcnt(0)
	v_pk_add_f32 v[146:147], v[140:141], 1.0 op_sel_hi:[1,0]
	v_pk_add_f32 v[140:141], v[150:151], 1.0 op_sel_hi:[1,0]
	v_lshl_add_u32 v150, s29, 8, v154
	v_ashrrev_i32_e32 v151, 31, v150
	v_pk_add_f32 v[144:145], v[142:143], 1.0 op_sel_hi:[1,0]
	v_pk_add_f32 v[142:143], v[148:149], 1.0 op_sel_hi:[1,0]
	v_lshlrev_b64 v[148:149], 12, v[150:151]
	v_lshl_add_u64 v[148:149], s[50:51], 0, v[148:149]
	v_lshl_add_u64 v[148:149], v[148:149], 0, v[152:153]
	v_lshl_add_u32 v184, v150, 12, v152
	s_add_u32 s100, s50, 0
	s_addc_u32 s101, s51, 0
	global_load_dwordx4 v[176:179], v184, s[100:101]
	s_add_u32 s100, s100, 0x10000
	s_addc_u32 s101, s101, 0
	global_load_dwordx4 v[180:183], v184, s[100:101]
	s_add_u32 s100, s100, 0x10000
	s_addc_u32 s101, s101, 0
	global_load_dwordx4 v[188:191], v184, s[100:101]
	s_add_u32 s100, s100, 0x10000
	s_addc_u32 s101, s101, 0
	global_load_dwordx4 v[192:195], v184, s[100:101]
	s_add_u32 s100, s100, 0x50000
	s_addc_u32 s101, s101, 0
	global_load_dwordx4 v[196:199], v184, s[100:101]
	s_add_u32 s100, s100, 0x10000
	s_addc_u32 s101, s101, 0
	global_load_dwordx4 v[200:203], v184, s[100:101]
	s_add_u32 s100, s100, 0x10000
	s_addc_u32 s101, s101, 0
	global_load_dwordx4 v[204:207], v184, s[100:101]
	s_add_u32 s100, s100, 0x10000
	s_addc_u32 s101, s101, 0
	global_load_dwordx4 v[218:221], v184, s[100:101]
	v_exp_f32_e32 v86, v86
	v_exp_f32_e32 v82, v82
	v_exp_f32_e32 v87, v87
	v_exp_f32_e32 v83, v83
	v_exp_f32_e32 v88, v88
	v_exp_f32_e32 v84, v84
	v_exp_f32_e32 v89, v89
	v_exp_f32_e32 v85, v85
	v_add_f32_e32 v86, 1.0, v86
	v_add_f32_e32 v82, 1.0, v82
	v_add_f32_e32 v87, 1.0, v87
	v_add_f32_e32 v83, 1.0, v83
	v_add_f32_e32 v88, 1.0, v88
	v_add_f32_e32 v84, 1.0, v84
	v_add_f32_e32 v89, 1.0, v89
	v_add_f32_e32 v85, 1.0, v85
	v_rcp_f32_e32 v86, v86
	v_rcp_f32_e32 v82, v82
	v_rcp_f32_e32 v87, v87
	v_rcp_f32_e32 v83, v83
	v_rcp_f32_e32 v88, v88
	v_rcp_f32_e32 v84, v84
	v_rcp_f32_e32 v89, v89
	v_rcp_f32_e32 v85, v85
	v_pk_mul_f32 v[86:87], v[94:95], v[86:87]
	v_pk_mul_f32 v[82:83], v[90:91], v[82:83]
	v_pk_mul_f32 v[88:89], v[96:97], v[88:89]
	v_pk_mul_f32 v[84:85], v[92:93], v[84:85]
	v_mul_f32_e32 v70, 0xbfb8aa3b, v70
	v_mul_f32_e32 v66, 0xbfb8aa3b, v66
	v_mul_f32_e32 v71, 0xbfb8aa3b, v71
	v_mul_f32_e32 v67, 0xbfb8aa3b, v67
	v_mul_f32_e32 v72, 0xbfb8aa3b, v72
	v_mul_f32_e32 v68, 0xbfb8aa3b, v68
	v_mul_f32_e32 v73, 0xbfb8aa3b, v73
	v_mul_f32_e32 v69, 0xbfb8aa3b, v69
	v_exp_f32_e32 v70, v70
	v_exp_f32_e32 v66, v66
	v_exp_f32_e32 v71, v71
	v_exp_f32_e32 v67, v67
	v_exp_f32_e32 v72, v72
	v_exp_f32_e32 v68, v68
	v_exp_f32_e32 v73, v73
	v_exp_f32_e32 v69, v69
	v_add_f32_e32 v70, 1.0, v70
	v_add_f32_e32 v66, 1.0, v66
	v_add_f32_e32 v71, 1.0, v71
	v_add_f32_e32 v67, 1.0, v67
	v_add_f32_e32 v72, 1.0, v72
	v_add_f32_e32 v68, 1.0, v68
	v_add_f32_e32 v73, 1.0, v73
	v_add_f32_e32 v69, 1.0, v69
	v_rcp_f32_e32 v70, v70
	v_rcp_f32_e32 v66, v66
	v_rcp_f32_e32 v71, v71
	v_rcp_f32_e32 v67, v67
	v_rcp_f32_e32 v72, v72
	v_rcp_f32_e32 v68, v68
	v_rcp_f32_e32 v73, v73
	v_rcp_f32_e32 v69, v69
	v_pk_mul_f32 v[70:71], v[78:79], v[70:71]
	v_pk_mul_f32 v[66:67], v[74:75], v[66:67]
	v_pk_mul_f32 v[72:73], v[80:81], v[72:73]
	v_pk_mul_f32 v[68:69], v[76:77], v[68:69]
	s_mov_b32 s3, 0x80000
	v_mul_f32_e32 v54, 0xbfb8aa3b, v54
	v_mul_f32_e32 v50, 0xbfb8aa3b, v50
	v_mul_f32_e32 v55, 0xbfb8aa3b, v55
	v_mul_f32_e32 v51, 0xbfb8aa3b, v51
	v_mul_f32_e32 v56, 0xbfb8aa3b, v56
	v_mul_f32_e32 v52, 0xbfb8aa3b, v52
	v_mul_f32_e32 v57, 0xbfb8aa3b, v57
	v_mul_f32_e32 v53, 0xbfb8aa3b, v53
	v_exp_f32_e32 v54, v54
	v_exp_f32_e32 v50, v50
	v_exp_f32_e32 v55, v55
	v_exp_f32_e32 v51, v51
	v_exp_f32_e32 v56, v56
	v_exp_f32_e32 v52, v52
	s_waitcnt vmcnt(0)
	v_lshlrev_b32_e32 v162, 16, v176
	v_and_b32_e32 v163, 0xffff0000, v176
	v_lshlrev_b32_e32 v158, 16, v177
	v_and_b32_e32 v159, 0xffff0000, v177
	v_lshlrev_b32_e32 v164, 16, v178
	v_and_b32_e32 v165, 0xffff0000, v178
	v_lshlrev_b32_e32 v160, 16, v179
	v_and_b32_e32 v161, 0xffff0000, v179
	v_pk_mul_f32 v[122:123], v[162:163], s[60:61] op_sel_hi:[1,0]
	v_pk_mul_f32 v[124:125], v[158:159], s[60:61] op_sel_hi:[1,0]
	v_pk_fma_f32 v[118:119], v[118:119], v[146:147], v[122:123]
	v_pk_fma_f32 v[120:121], v[120:121], v[144:145], v[124:125]
	v_pk_mul_f32 v[122:123], v[164:165], s[60:61] op_sel_hi:[1,0]
	v_pk_mul_f32 v[124:125], v[160:161], s[60:61] op_sel_hi:[1,0]
	v_exp_f32_e32 v57, v57
	v_pk_fma_f32 v[124:125], v[116:117], v[140:141], v[124:125]
	v_pk_fma_f32 v[116:117], v[114:115], v[142:143], v[122:123]
	v_cvt_pk_bf16_f32 v114, v118, v119
	v_cvt_pk_bf16_f32 v115, v120, v121
	v_cvt_pk_bf16_f32 v116, v116, v117
	v_cvt_pk_bf16_f32 v117, v124, v125
	global_store_dwordx4 v[148:149], v[114:117], off
	v_exp_f32_e32 v53, v53
	v_add_f32_e32 v54, 1.0, v54
	v_or_b32_e32 v114, 16, v150
	v_ashrrev_i32_e32 v115, 31, v114
	v_lshlrev_b64 v[114:115], 12, v[114:115]
	v_lshl_add_u64 v[114:115], s[50:51], 0, v[114:115]
	v_lshl_add_u64 v[118:119], v[114:115], 0, v[152:153]
	v_add_f32_e32 v50, 1.0, v50
	v_add_f32_e32 v55, 1.0, v55
	v_add_f32_e32 v51, 1.0, v51
	v_add_f32_e32 v56, 1.0, v56
	v_add_f32_e32 v52, 1.0, v52
	v_add_f32_e32 v57, 1.0, v57
	v_add_f32_e32 v53, 1.0, v53
	v_rcp_f32_e32 v54, v54
	v_rcp_f32_e32 v50, v50
	v_rcp_f32_e32 v55, v55
	v_rcp_f32_e32 v51, v51
	v_rcp_f32_e32 v56, v56
	v_rcp_f32_e32 v52, v52
	v_rcp_f32_e32 v57, v57
	v_rcp_f32_e32 v53, v53
	v_pk_mul_f32 v[54:55], v[62:63], v[54:55]
	v_pk_mul_f32 v[50:51], v[58:59], v[50:51]
	v_pk_mul_f32 v[56:57], v[64:65], v[56:57]
	v_pk_mul_f32 v[52:53], v[60:61], v[52:53]
	v_mul_f32_e32 v38, 0xbfb8aa3b, v38
	v_mul_f32_e32 v34, 0xbfb8aa3b, v34
	v_mul_f32_e32 v39, 0xbfb8aa3b, v39
	v_mul_f32_e32 v35, 0xbfb8aa3b, v35
	v_mul_f32_e32 v40, 0xbfb8aa3b, v40
	v_mul_f32_e32 v36, 0xbfb8aa3b, v36
	v_mul_f32_e32 v41, 0xbfb8aa3b, v41
	v_mul_f32_e32 v37, 0xbfb8aa3b, v37
	v_exp_f32_e32 v38, v38
	v_exp_f32_e32 v34, v34
	v_exp_f32_e32 v39, v39
	v_exp_f32_e32 v35, v35
	v_exp_f32_e32 v40, v40
	v_exp_f32_e32 v36, v36
	v_exp_f32_e32 v41, v41
	v_exp_f32_e32 v37, v37
	v_add_f32_e32 v38, 1.0, v38
	v_add_f32_e32 v34, 1.0, v34
	v_add_f32_e32 v39, 1.0, v39
	v_add_f32_e32 v35, 1.0, v35
	v_add_f32_e32 v40, 1.0, v40
	v_add_f32_e32 v36, 1.0, v36
	v_add_f32_e32 v41, 1.0, v41
	v_add_f32_e32 v37, 1.0, v37
	v_rcp_f32_e32 v38, v38
	v_rcp_f32_e32 v34, v34
	v_rcp_f32_e32 v39, v39
	v_rcp_f32_e32 v35, v35
	v_rcp_f32_e32 v40, v40
	v_rcp_f32_e32 v36, v36
	v_rcp_f32_e32 v41, v41
	v_rcp_f32_e32 v37, v37
	v_pk_mul_f32 v[38:39], v[46:47], v[38:39]
	v_pk_mul_f32 v[34:35], v[42:43], v[34:35]
	v_pk_mul_f32 v[40:41], v[48:49], v[40:41]
	v_pk_mul_f32 v[36:37], v[44:45], v[36:37]
	v_mul_f32_e32 v22, 0xbfb8aa3b, v22
	v_mul_f32_e32 v18, 0xbfb8aa3b, v18
	v_mul_f32_e32 v23, 0xbfb8aa3b, v23
	v_mul_f32_e32 v19, 0xbfb8aa3b, v19
	v_mul_f32_e32 v24, 0xbfb8aa3b, v24
	v_mul_f32_e32 v20, 0xbfb8aa3b, v20
	v_mul_f32_e32 v25, 0xbfb8aa3b, v25
	v_mul_f32_e32 v21, 0xbfb8aa3b, v21
	v_exp_f32_e32 v22, v22
	v_exp_f32_e32 v18, v18
	v_exp_f32_e32 v23, v23
	v_exp_f32_e32 v19, v19
	v_exp_f32_e32 v24, v24
	v_exp_f32_e32 v20, v20
	v_exp_f32_e32 v25, v25
	v_exp_f32_e32 v21, v21
	v_add_f32_e32 v22, 1.0, v22
	v_add_f32_e32 v18, 1.0, v18
	v_add_f32_e32 v23, 1.0, v23
	v_add_f32_e32 v19, 1.0, v19
	v_add_f32_e32 v24, 1.0, v24
	v_add_f32_e32 v20, 1.0, v20
	v_add_f32_e32 v25, 1.0, v25
	v_add_f32_e32 v21, 1.0, v21
	v_lshlrev_b32_e32 v120, 16, v180
	v_and_b32_e32 v121, 0xffff0000, v180
	v_lshlrev_b32_e32 v114, 16, v181
	v_and_b32_e32 v115, 0xffff0000, v181
	v_lshlrev_b32_e32 v122, 16, v182
	v_and_b32_e32 v123, 0xffff0000, v182
	v_lshlrev_b32_e32 v116, 16, v183
	v_and_b32_e32 v117, 0xffff0000, v183
	v_pk_mul_f32 v[106:107], v[120:121], s[60:61] op_sel_hi:[1,0]
	v_pk_mul_f32 v[108:109], v[114:115], s[60:61] op_sel_hi:[1,0]
	v_pk_fma_f32 v[102:103], v[102:103], v[146:147], v[106:107]
	v_pk_fma_f32 v[104:105], v[104:105], v[144:145], v[108:109]
	v_pk_mul_f32 v[106:107], v[122:123], s[60:61] op_sel_hi:[1,0]
	v_pk_mul_f32 v[108:109], v[116:117], s[60:61] op_sel_hi:[1,0]
	v_rcp_f32_e32 v22, v22
	v_pk_fma_f32 v[108:109], v[100:101], v[140:141], v[108:109]
	v_pk_fma_f32 v[100:101], v[98:99], v[142:143], v[106:107]
	v_cvt_pk_bf16_f32 v98, v102, v103
	v_cvt_pk_bf16_f32 v99, v104, v105
	v_cvt_pk_bf16_f32 v100, v100, v101
	v_cvt_pk_bf16_f32 v101, v108, v109
	global_store_dwordx4 v[118:119], v[98:101], off
	v_rcp_f32_e32 v18, v18
	v_rcp_f32_e32 v23, v23
	v_or_b32_e32 v98, 32, v150
	v_ashrrev_i32_e32 v99, 31, v98
	v_lshlrev_b64 v[98:99], 12, v[98:99]
	v_lshl_add_u64 v[98:99], s[50:51], 0, v[98:99]
	v_lshl_add_u64 v[102:103], v[98:99], 0, v[152:153]
	v_rcp_f32_e32 v19, v19
	v_rcp_f32_e32 v24, v24
	v_rcp_f32_e32 v20, v20
	v_rcp_f32_e32 v25, v25
	v_rcp_f32_e32 v21, v21
	v_pk_mul_f32 v[22:23], v[30:31], v[22:23]
	v_pk_mul_f32 v[18:19], v[26:27], v[18:19]
	v_pk_mul_f32 v[24:25], v[32:33], v[24:25]
	v_pk_mul_f32 v[20:21], v[28:29], v[20:21]
	v_mul_f32_e32 v10, 0xbfb8aa3b, v10
	v_mul_f32_e32 v2, 0xbfb8aa3b, v2
	v_mul_f32_e32 v11, 0xbfb8aa3b, v11
	v_mul_f32_e32 v3, 0xbfb8aa3b, v3
	v_mul_f32_e32 v12, 0xbfb8aa3b, v12
	v_mul_f32_e32 v4, 0xbfb8aa3b, v4
	v_mul_f32_e32 v13, 0xbfb8aa3b, v13
	v_mul_f32_e32 v5, 0xbfb8aa3b, v5
	v_exp_f32_e32 v10, v10
	v_exp_f32_e32 v2, v2
	v_exp_f32_e32 v11, v11
	v_exp_f32_e32 v3, v3
	v_exp_f32_e32 v12, v12
	v_exp_f32_e32 v4, v4
	v_exp_f32_e32 v13, v13
	v_exp_f32_e32 v5, v5
	v_add_f32_e32 v10, 1.0, v10
	v_add_f32_e32 v2, 1.0, v2
	v_add_f32_e32 v11, 1.0, v11
	v_add_f32_e32 v3, 1.0, v3
	v_add_f32_e32 v12, 1.0, v12
	v_add_f32_e32 v4, 1.0, v4
	v_add_f32_e32 v13, 1.0, v13
	v_add_f32_e32 v5, 1.0, v5
	v_rcp_f32_e32 v10, v10
	v_rcp_f32_e32 v2, v2
	v_rcp_f32_e32 v11, v11
	v_rcp_f32_e32 v3, v3
	v_rcp_f32_e32 v12, v12
	v_rcp_f32_e32 v4, v4
	v_rcp_f32_e32 v13, v13
	v_rcp_f32_e32 v5, v5
	v_pk_mul_f32 v[10:11], v[14:15], v[10:11]
	v_pk_mul_f32 v[2:3], v[6:7], v[2:3]
	v_pk_mul_f32 v[12:13], v[16:17], v[12:13]
	v_pk_mul_f32 v[4:5], v[8:9], v[4:5]
	s_mov_b64 s[16:17], -1
	s_mov_b32 s44, 0x8000
	s_mov_b32 s45, 0xa000
	v_lshlrev_b32_e32 v104, 16, v188
	v_and_b32_e32 v105, 0xffff0000, v188
	v_lshlrev_b32_e32 v98, 16, v189
	v_and_b32_e32 v99, 0xffff0000, v189
	v_lshlrev_b32_e32 v106, 16, v190
	v_and_b32_e32 v107, 0xffff0000, v190
	v_lshlrev_b32_e32 v100, 16, v191
	v_and_b32_e32 v101, 0xffff0000, v191
	v_pk_mul_f32 v[90:91], v[104:105], s[60:61] op_sel_hi:[1,0]
	v_pk_mul_f32 v[92:93], v[98:99], s[60:61] op_sel_hi:[1,0]
	v_pk_fma_f32 v[86:87], v[86:87], v[146:147], v[90:91]
	v_pk_fma_f32 v[88:89], v[88:89], v[144:145], v[92:93]
	v_pk_mul_f32 v[90:91], v[106:107], s[60:61] op_sel_hi:[1,0]
	v_pk_mul_f32 v[92:93], v[100:101], s[60:61] op_sel_hi:[1,0]
	s_nop 0
	v_pk_fma_f32 v[92:93], v[84:85], v[140:141], v[92:93]
	v_pk_fma_f32 v[84:85], v[82:83], v[142:143], v[90:91]
	v_cvt_pk_bf16_f32 v82, v86, v87
	v_cvt_pk_bf16_f32 v83, v88, v89
	v_cvt_pk_bf16_f32 v84, v84, v85
	v_cvt_pk_bf16_f32 v85, v92, v93
	global_store_dwordx4 v[102:103], v[82:85], off
	s_nop 1
	v_or_b32_e32 v82, 48, v150
	v_ashrrev_i32_e32 v83, 31, v82
	v_lshlrev_b64 v[82:83], 12, v[82:83]
	v_lshl_add_u64 v[82:83], s[50:51], 0, v[82:83]
	v_lshl_add_u64 v[86:87], v[82:83], 0, v[152:153]
	v_lshlrev_b32_e32 v88, 16, v192
	v_and_b32_e32 v89, 0xffff0000, v192
	v_lshlrev_b32_e32 v82, 16, v193
	v_and_b32_e32 v83, 0xffff0000, v193
	v_lshlrev_b32_e32 v90, 16, v194
	v_and_b32_e32 v91, 0xffff0000, v194
	v_lshlrev_b32_e32 v84, 16, v195
	v_and_b32_e32 v85, 0xffff0000, v195
	v_pk_mul_f32 v[74:75], v[88:89], s[60:61] op_sel_hi:[1,0]
	v_pk_mul_f32 v[76:77], v[82:83], s[60:61] op_sel_hi:[1,0]
	v_pk_fma_f32 v[70:71], v[70:71], v[146:147], v[74:75]
	v_pk_fma_f32 v[72:73], v[72:73], v[144:145], v[76:77]
	v_pk_mul_f32 v[74:75], v[90:91], s[60:61] op_sel_hi:[1,0]
	v_pk_mul_f32 v[76:77], v[84:85], s[60:61] op_sel_hi:[1,0]
	s_nop 0
	v_pk_fma_f32 v[76:77], v[68:69], v[140:141], v[76:77]
	v_pk_fma_f32 v[68:69], v[66:67], v[142:143], v[74:75]
	v_cvt_pk_bf16_f32 v66, v70, v71
	v_add_co_u32_e32 v70, vcc, s3, v148
	v_cvt_pk_bf16_f32 v67, v72, v73
	v_cvt_pk_bf16_f32 v68, v68, v69
	v_cvt_pk_bf16_f32 v69, v76, v77
	v_addc_co_u32_e32 v71, vcc, 0, v149, vcc
	global_store_dwordx4 v[86:87], v[66:69], off
	s_mov_b32 s3, 0x90000
	v_lshlrev_b32_e32 v72, 16, v196
	v_and_b32_e32 v73, 0xffff0000, v196
	v_lshlrev_b32_e32 v66, 16, v197
	v_and_b32_e32 v67, 0xffff0000, v197
	v_lshlrev_b32_e32 v74, 16, v198
	v_and_b32_e32 v75, 0xffff0000, v198
	v_lshlrev_b32_e32 v68, 16, v199
	v_and_b32_e32 v69, 0xffff0000, v199
	v_pk_mul_f32 v[58:59], v[72:73], s[60:61] op_sel_hi:[1,0]
	v_pk_mul_f32 v[60:61], v[66:67], s[60:61] op_sel_hi:[1,0]
	v_pk_fma_f32 v[54:55], v[54:55], v[146:147], v[58:59]
	v_pk_fma_f32 v[56:57], v[56:57], v[144:145], v[60:61]
	v_pk_mul_f32 v[58:59], v[74:75], s[60:61] op_sel_hi:[1,0]
	v_pk_mul_f32 v[60:61], v[68:69], s[60:61] op_sel_hi:[1,0]
	s_nop 0
	v_pk_fma_f32 v[60:61], v[52:53], v[140:141], v[60:61]
	v_pk_fma_f32 v[52:53], v[50:51], v[142:143], v[58:59]
	v_cvt_pk_bf16_f32 v50, v54, v55
	v_add_co_u32_e32 v54, vcc, s3, v148
	v_cvt_pk_bf16_f32 v51, v56, v57
	v_cvt_pk_bf16_f32 v52, v52, v53
	v_cvt_pk_bf16_f32 v53, v60, v61
	v_addc_co_u32_e32 v55, vcc, 0, v149, vcc
	global_store_dwordx4 v[70:71], v[50:53], off
	s_mov_b32 s3, 0xa0000
	v_lshlrev_b32_e32 v56, 16, v200
	v_and_b32_e32 v57, 0xffff0000, v200
	v_lshlrev_b32_e32 v50, 16, v201
	v_and_b32_e32 v51, 0xffff0000, v201
	v_lshlrev_b32_e32 v58, 16, v202
	v_and_b32_e32 v59, 0xffff0000, v202
	v_lshlrev_b32_e32 v52, 16, v203
	v_and_b32_e32 v53, 0xffff0000, v203
	v_pk_mul_f32 v[42:43], v[56:57], s[60:61] op_sel_hi:[1,0]
	v_pk_mul_f32 v[44:45], v[50:51], s[60:61] op_sel_hi:[1,0]
	v_pk_fma_f32 v[38:39], v[38:39], v[146:147], v[42:43]
	v_pk_fma_f32 v[40:41], v[40:41], v[144:145], v[44:45]
	v_pk_mul_f32 v[42:43], v[58:59], s[60:61] op_sel_hi:[1,0]
	v_pk_mul_f32 v[44:45], v[52:53], s[60:61] op_sel_hi:[1,0]
	s_nop 0
	v_pk_fma_f32 v[44:45], v[36:37], v[140:141], v[44:45]
	v_pk_fma_f32 v[36:37], v[34:35], v[142:143], v[42:43]
	v_cvt_pk_bf16_f32 v34, v38, v39
	v_add_co_u32_e32 v38, vcc, s3, v148
	v_cvt_pk_bf16_f32 v35, v40, v41
	v_cvt_pk_bf16_f32 v36, v36, v37
	v_cvt_pk_bf16_f32 v37, v44, v45
	v_addc_co_u32_e32 v39, vcc, 0, v149, vcc
	global_store_dwordx4 v[54:55], v[34:37], off
	s_mov_b32 s3, 0xb0000
	v_lshlrev_b32_e32 v40, 16, v204
	v_and_b32_e32 v41, 0xffff0000, v204
	v_lshlrev_b32_e32 v34, 16, v205
	v_and_b32_e32 v35, 0xffff0000, v205
	v_lshlrev_b32_e32 v42, 16, v206
	v_and_b32_e32 v43, 0xffff0000, v206
	v_lshlrev_b32_e32 v36, 16, v207
	v_and_b32_e32 v37, 0xffff0000, v207
	v_pk_mul_f32 v[26:27], v[40:41], s[60:61] op_sel_hi:[1,0]
	v_pk_mul_f32 v[28:29], v[34:35], s[60:61] op_sel_hi:[1,0]
	v_pk_fma_f32 v[22:23], v[22:23], v[146:147], v[26:27]
	v_pk_fma_f32 v[24:25], v[24:25], v[144:145], v[28:29]
	v_pk_mul_f32 v[26:27], v[42:43], s[60:61] op_sel_hi:[1,0]
	v_pk_mul_f32 v[28:29], v[36:37], s[60:61] op_sel_hi:[1,0]
	s_nop 0
	v_pk_fma_f32 v[28:29], v[20:21], v[140:141], v[28:29]
	v_pk_fma_f32 v[20:21], v[18:19], v[142:143], v[26:27]
	v_cvt_pk_bf16_f32 v18, v22, v23
	v_add_co_u32_e32 v22, vcc, s3, v148
	v_cvt_pk_bf16_f32 v19, v24, v25
	v_cvt_pk_bf16_f32 v20, v20, v21
	v_cvt_pk_bf16_f32 v21, v28, v29
	v_addc_co_u32_e32 v23, vcc, 0, v149, vcc
	global_store_dwordx4 v[38:39], v[18:21], off
	s_andn2_b64 vcc, exec, s[0:1]
	v_lshlrev_b32_e32 v24, 16, v218
	v_and_b32_e32 v25, 0xffff0000, v218
	v_lshlrev_b32_e32 v18, 16, v219
	v_and_b32_e32 v19, 0xffff0000, v219
	v_lshlrev_b32_e32 v26, 16, v220
	v_and_b32_e32 v27, 0xffff0000, v220
	v_lshlrev_b32_e32 v20, 16, v221
	v_and_b32_e32 v21, 0xffff0000, v221
	v_pk_mul_f32 v[6:7], v[24:25], s[60:61] op_sel_hi:[1,0]
	v_pk_mul_f32 v[8:9], v[18:19], s[60:61] op_sel_hi:[1,0]
	v_pk_fma_f32 v[6:7], v[10:11], v[146:147], v[6:7]
	v_pk_fma_f32 v[8:9], v[12:13], v[144:145], v[8:9]
	v_pk_mul_f32 v[10:11], v[26:27], s[60:61] op_sel_hi:[1,0]
	v_pk_mul_f32 v[12:13], v[20:21], s[60:61] op_sel_hi:[1,0]
	s_nop 0
	v_pk_fma_f32 v[12:13], v[4:5], v[140:141], v[12:13]
	v_pk_fma_f32 v[4:5], v[2:3], v[142:143], v[10:11]
	v_cvt_pk_bf16_f32 v2, v6, v7
	v_cvt_pk_bf16_f32 v3, v8, v9
	v_cvt_pk_bf16_f32 v4, v4, v5
	v_cvt_pk_bf16_f32 v5, v12, v13
	global_store_dwordx4 v[22:23], v[2:5], off
	s_cbranch_vccnz .LBB0_369
	s_andn2_b64 vcc, exec, s[4:5]
	s_cbranch_vccnz .LBB0_368
	s_barrier
	s_branch .LBB0_368
